# MFMA-VALU interleave in CL: the 32 row-sum adds placed one behind each PV MFMA (placement phases of all hot loops unchanged)
# speedup vs baseline: 1.0029x; 1.0029x over previous
.LBB0_459:
	v_pk_fma_f32 v[142:143], v[142:143], s[42:43], v[216:217] op_sel:[0,0,1] op_sel_hi:[1,0,1] neg_lo:[0,0,1] neg_hi:[0,0,1]
	v_pk_fma_f32 v[144:145], v[144:145], s[42:43], v[216:217] op_sel:[0,0,1] op_sel_hi:[1,0,1] neg_lo:[0,0,1] neg_hi:[0,0,1]
	v_pk_fma_f32 v[134:135], v[134:135], s[42:43], v[216:217] op_sel:[0,0,1] op_sel_hi:[1,0,1] neg_lo:[0,0,1] neg_hi:[0,0,1]
	v_pk_fma_f32 v[136:137], v[136:137], s[42:43], v[216:217] op_sel:[0,0,1] op_sel_hi:[1,0,1] neg_lo:[0,0,1] neg_hi:[0,0,1]
	v_pk_fma_f32 v[126:127], v[126:127], s[42:43], v[216:217] op_sel:[0,0,1] op_sel_hi:[1,0,1] neg_lo:[0,0,1] neg_hi:[0,0,1]
	v_pk_fma_f32 v[128:129], v[128:129], s[42:43], v[216:217] op_sel:[0,0,1] op_sel_hi:[1,0,1] neg_lo:[0,0,1] neg_hi:[0,0,1]
	v_pk_fma_f32 v[118:119], v[118:119], s[42:43], v[216:217] op_sel:[0,0,1] op_sel_hi:[1,0,1] neg_lo:[0,0,1] neg_hi:[0,0,1]
	v_pk_fma_f32 v[120:121], v[120:121], s[42:43], v[216:217] op_sel:[0,0,1] op_sel_hi:[1,0,1] neg_lo:[0,0,1] neg_hi:[0,0,1]
	v_pk_fma_f32 v[138:139], v[138:139], s[42:43], v[218:219] op_sel_hi:[1,0,0] neg_lo:[0,0,1] neg_hi:[0,0,1]
	v_pk_fma_f32 v[140:141], v[140:141], s[42:43], v[218:219] op_sel_hi:[1,0,0] neg_lo:[0,0,1] neg_hi:[0,0,1]
	v_pk_fma_f32 v[130:131], v[130:131], s[42:43], v[218:219] op_sel_hi:[1,0,0] neg_lo:[0,0,1] neg_hi:[0,0,1]
	v_pk_fma_f32 v[132:133], v[132:133], s[42:43], v[218:219] op_sel_hi:[1,0,0] neg_lo:[0,0,1] neg_hi:[0,0,1]
	v_pk_fma_f32 v[122:123], v[122:123], s[42:43], v[218:219] op_sel_hi:[1,0,0] neg_lo:[0,0,1] neg_hi:[0,0,1]
	v_pk_fma_f32 v[124:125], v[124:125], s[42:43], v[218:219] op_sel_hi:[1,0,0] neg_lo:[0,0,1] neg_hi:[0,0,1]
	v_pk_fma_f32 v[114:115], v[114:115], s[42:43], v[218:219] op_sel_hi:[1,0,0] neg_lo:[0,0,1] neg_hi:[0,0,1]
	v_pk_fma_f32 v[116:117], v[116:117], s[42:43], v[218:219] op_sel_hi:[1,0,0] neg_lo:[0,0,1] neg_hi:[0,0,1]
	v_exp_f32_e32 v142, v142
	v_exp_f32_e32 v143, v143
	v_exp_f32_e32 v144, v144
	v_exp_f32_e32 v145, v145
	v_exp_f32_e32 v134, v134
	v_exp_f32_e32 v135, v135
	v_exp_f32_e32 v136, v136
	v_exp_f32_e32 v137, v137
	v_exp_f32_e32 v126, v126
	v_exp_f32_e32 v127, v127
	v_exp_f32_e32 v128, v128
	v_exp_f32_e32 v129, v129
	v_exp_f32_e32 v118, v118
	v_exp_f32_e32 v119, v119
	v_exp_f32_e32 v120, v120
	v_exp_f32_e32 v121, v121
	v_exp_f32_e32 v138, v138
	v_exp_f32_e32 v139, v139
	v_exp_f32_e32 v140, v140
	v_exp_f32_e32 v141, v141
	v_exp_f32_e32 v130, v130
	v_exp_f32_e32 v131, v131
	v_exp_f32_e32 v132, v132
	v_exp_f32_e32 v133, v133
	v_exp_f32_e32 v122, v122
	v_exp_f32_e32 v123, v123
	v_exp_f32_e32 v124, v124
	v_exp_f32_e32 v125, v125
	v_exp_f32_e32 v114, v114
	v_exp_f32_e32 v115, v115
	v_exp_f32_e32 v116, v116
	v_exp_f32_e32 v117, v117
	v_cvt_pk_bf16_f32 v196, v142, v143
	v_cvt_pk_bf16_f32 v197, v144, v145
	v_cvt_pk_bf16_f32 v198, v134, v135
	v_cvt_pk_bf16_f32 v199, v136, v137
	v_cvt_pk_bf16_f32 v200, v126, v127
	v_cvt_pk_bf16_f32 v201, v128, v129
	v_cvt_pk_bf16_f32 v202, v118, v119
	v_cvt_pk_bf16_f32 v203, v120, v121
	v_cvt_pk_bf16_f32 v204, v138, v139
	v_cvt_pk_bf16_f32 v205, v140, v141
	v_cvt_pk_bf16_f32 v206, v130, v131
	v_cvt_pk_bf16_f32 v207, v132, v133
	v_cvt_pk_bf16_f32 v208, v122, v123
	v_cvt_pk_bf16_f32 v209, v124, v125
	v_cvt_pk_bf16_f32 v210, v114, v115
	v_cvt_pk_bf16_f32 v211, v116, v117
	ds_read_b64_tr_b16 v[222:223], v17 offset:21056
	ds_read_b64_tr_b16 v[220:221], v17 offset:16448
	ds_read_b64_tr_b16 v[226:227], v17 offset:21088
	ds_read_b64_tr_b16 v[224:225], v17 offset:16480
	ds_read_b64_tr_b16 v[228:229], v17 offset:25664
	ds_read_b64_tr_b16 v[230:231], v17 offset:30272
	ds_read_b64_tr_b16 v[234:235], v17 offset:30304
	ds_read_b64_tr_b16 v[232:233], v17 offset:25696
	s_waitcnt lgkmcnt(8)
	v_mfma_f32_16x16x32_bf16 v[70:73], v[102:105], v[196:199], v[70:73]
	v_add_f32_e32 v252, 0, v138
	v_mfma_f32_16x16x32_bf16 v[78:81], v[102:105], v[204:207], v[78:81]
	v_add_f32_e32 v253, 0, v142
	v_mfma_f32_16x16x32_bf16 v[66:69], v[98:101], v[196:199], v[66:69]
	v_add_f32_e32 v252, v139, v252
	v_mfma_f32_16x16x32_bf16 v[74:77], v[98:101], v[204:207], v[74:77]
	v_add_f32_e32 v253, v143, v253
	v_mfma_f32_16x16x32_bf16 v[70:73], v[106:109], v[200:203], v[70:73]
	v_add_f32_e32 v252, v140, v252
	v_mfma_f32_16x16x32_bf16 v[78:81], v[106:109], v[208:211], v[78:81]
	v_add_f32_e32 v253, v144, v253
	v_mfma_f32_16x16x32_bf16 v[66:69], v[110:113], v[200:203], v[66:69]
	v_add_f32_e32 v252, v141, v252
	v_mfma_f32_16x16x32_bf16 v[74:77], v[110:113], v[208:211], v[74:77]
	v_add_f32_e32 v253, v145, v253
	ds_read_b64_tr_b16 v[100:101], v17 offset:21120
	ds_read_b64_tr_b16 v[98:99], v17 offset:16512
	ds_read_b64_tr_b16 v[104:105], v17 offset:21152
	ds_read_b64_tr_b16 v[102:103], v17 offset:16544
	ds_read_b64_tr_b16 v[106:107], v17 offset:25728
	ds_read_b64_tr_b16 v[108:109], v17 offset:30336
	ds_read_b64_tr_b16 v[112:113], v17 offset:30368
	ds_read_b64_tr_b16 v[110:111], v17 offset:25760
	s_waitcnt lgkmcnt(14)
	v_mfma_f32_16x16x32_bf16 v[54:57], v[220:223], v[196:199], v[54:57]
	v_add_f32_e32 v252, v130, v252
	v_mfma_f32_16x16x32_bf16 v[62:65], v[220:223], v[204:207], v[62:65]
	v_add_f32_e32 v253, v134, v253
	s_waitcnt lgkmcnt(12)
	v_mfma_f32_16x16x32_bf16 v[50:53], v[224:227], v[196:199], v[50:53]
	v_add_f32_e32 v252, v131, v252
	v_mfma_f32_16x16x32_bf16 v[58:61], v[224:227], v[204:207], v[58:61]
	v_add_f32_e32 v253, v135, v253
	s_waitcnt lgkmcnt(10)
	v_mfma_f32_16x16x32_bf16 v[54:57], v[228:231], v[200:203], v[54:57]
	v_add_f32_e32 v252, v132, v252
	v_mfma_f32_16x16x32_bf16 v[62:65], v[228:231], v[208:211], v[62:65]
	v_add_f32_e32 v253, v136, v253
	s_waitcnt lgkmcnt(8)
	v_mfma_f32_16x16x32_bf16 v[50:53], v[232:235], v[200:203], v[50:53]
	v_add_f32_e32 v252, v133, v252
	v_mfma_f32_16x16x32_bf16 v[58:61], v[232:235], v[208:211], v[58:61]
	v_add_f32_e32 v253, v137, v253
	ds_read_b64_tr_b16 v[222:223], v17 offset:21184
	ds_read_b64_tr_b16 v[220:221], v17 offset:16576
	ds_read_b64_tr_b16 v[226:227], v17 offset:21216
	ds_read_b64_tr_b16 v[224:225], v17 offset:16608
	ds_read_b64_tr_b16 v[228:229], v17 offset:25792
	ds_read_b64_tr_b16 v[230:231], v17 offset:30400
	ds_read_b64_tr_b16 v[234:235], v17 offset:30432
	ds_read_b64_tr_b16 v[232:233], v17 offset:25824
	s_waitcnt lgkmcnt(14)
	v_mfma_f32_16x16x32_bf16 v[38:41], v[98:101], v[196:199], v[38:41]
	v_add_f32_e32 v252, v122, v252
	s_add_i32 s31, s30, 1
	s_cmp_ge_u32 s31, s29
	v_mfma_f32_16x16x32_bf16 v[46:49], v[98:101], v[204:207], v[46:49]
	v_add_f32_e32 v253, v126, v253
	s_waitcnt lgkmcnt(12)
	v_mfma_f32_16x16x32_bf16 v[34:37], v[102:105], v[196:199], v[34:37]
	v_add_f32_e32 v252, v123, v252
	v_mfma_f32_16x16x32_bf16 v[42:45], v[102:105], v[204:207], v[42:45]
	v_add_f32_e32 v253, v127, v253
	s_waitcnt lgkmcnt(6)
	v_mfma_f32_16x16x32_bf16 v[26:29], v[220:223], v[196:199], v[26:29]
	v_add_f32_e32 v252, v124, v252
	v_mfma_f32_16x16x32_bf16 v[30:33], v[220:223], v[204:207], v[30:33]
	v_add_f32_e32 v253, v128, v253
	s_waitcnt lgkmcnt(4)
	v_mfma_f32_16x16x32_bf16 v[22:25], v[224:227], v[196:199], v[22:25]
	v_add_f32_e32 v252, v125, v252
	v_mfma_f32_16x16x32_bf16 v[12:15], v[224:227], v[204:207], v[12:15]
	v_add_f32_e32 v253, v129, v253
	v_mfma_f32_16x16x32_bf16 v[38:41], v[106:109], v[200:203], v[38:41]
	v_add_f32_e32 v252, v114, v252
	v_mfma_f32_16x16x32_bf16 v[46:49], v[106:109], v[208:211], v[46:49]
	v_add_f32_e32 v253, v118, v253
	v_mfma_f32_16x16x32_bf16 v[34:37], v[110:113], v[200:203], v[34:37]
	v_add_f32_e32 v252, v115, v252
	v_mfma_f32_16x16x32_bf16 v[42:45], v[110:113], v[208:211], v[42:45]
	v_add_f32_e32 v253, v119, v253
	s_waitcnt lgkmcnt(2)
	v_mfma_f32_16x16x32_bf16 v[26:29], v[228:231], v[200:203], v[26:29]
	v_add_f32_e32 v252, v116, v252
	v_mfma_f32_16x16x32_bf16 v[30:33], v[228:231], v[208:211], v[30:33]
	v_add_f32_e32 v253, v120, v253
	s_waitcnt lgkmcnt(0)
	v_mfma_f32_16x16x32_bf16 v[22:25], v[232:235], v[200:203], v[22:25]
	v_add_f32_e32 v252, v117, v252
	v_mfma_f32_16x16x32_bf16 v[12:15], v[232:235], v[208:211], v[12:15]
	v_add_f32_e32 v253, v121, v253
	s_cbranch_scc1 .LBB0_461
	s_bitcmp1_b32 s31, 0
	s_cselect_b32 s48, 0x8800, 0
	s_add_i32 s48, s48, 0
	v_add3_u32 v17, s48, v147, v163
	v_add3_u32 v98, s48, v164, v165
	v_add3_u32 v99, s48, v170, v171
	v_add3_u32 v100, s48, v172, v171
	s_waitcnt vmcnt(3)
	ds_write_b128 v17, v[82:85]
	s_waitcnt vmcnt(2)
	ds_write_b128 v98, v[86:89]
	s_waitcnt vmcnt(1)
	ds_write_b128 v99, v[90:93] offset:16384
	s_waitcnt vmcnt(0)
	ds_write_b128 v100, v[94:97] offset:16384

.LBB0_463:
	v_cndmask_b32_e64 v98, v158, 1.0, s[10:11]
	v_mov_b32_e32 v17, v252
	v_fmac_f32_e32 v17, v216, v98
	v_cndmask_b32_e64 v99, v156, 1.0, s[8:9]
	v_mov_b32_e32 v98, v253
	v_fmac_f32_e32 v98, v215, v99
	s_cmp_lg_u32 s29, s31
	s_cbranch_scc0 .LBB0_465
	v_mov_b32_e32 v155, v218
	v_mov_b32_e32 v216, v17
	v_mov_b32_e32 v215, v98
	s_mov_b32 s30, s31
	s_branch .LBB0_455
